# final normalisation phase: read-once loads and write-once stores (full 1 KB per wave instruction) marked nt
# speedup vs baseline: 1.0067x; 1.0067x over previous
; __device__ __forceinline__ float rms_r(float ss) { return __builtin_amdgcn_rsqf(ss * (1.0f / DM) + RMS_EPS); }
; __device__ __forceinline__ void final_phase(float* out, const float* ss, const float* g) {
;     ...
;     for (int m0 = gw * 4; m0 < MT; m0 += NGW * 4) { f32x4 v[4][4]; float r[4];
; #pragma unroll
;         for (int q = 0; q < 4; ++q) { r[q] = ss[m0 + q];
; #pragma unroll
;             for (int j = 0; j < 4; ++j) v[q][j] = ((const f32x4*)(out + (size_t)(m0 + q) * DM))[lane + 64 * j]; }
; #pragma unroll
;         for (int q = 0; q < 4; ++q) { const float rr = rms_r(r[q]); f32x4* xr = (f32x4*)(out + (size_t)(m0 + q) * DM) + lane;
; #pragma unroll
;             for (int j = 0; j < 4; ++j) xr[64 * j] = v[q][j] * rr * gv[j]; } }
.LBB0_1858:
	global_load_dwordx4 v[22:25], v[18:19], off offset:-12
	v_add_co_u32_e32 v90, vcc, 0xffffd000, v20
	v_add_u32_e32 v16, s0, v16
	s_nop 0
	v_addc_co_u32_e32 v91, vcc, -1, v21, vcc
	v_add_co_u32_e32 v92, vcc, 0xffffe000, v20
	global_load_dwordx4 v[26:29], v[90:91], off offset:-3072 nt
	global_load_dwordx4 v[30:33], v[90:91], off offset:-2048 nt
	global_load_dwordx4 v[34:37], v[90:91], off offset:-1024 nt
	global_load_dwordx4 v[38:41], v[90:91], off nt
	v_addc_co_u32_e32 v93, vcc, -1, v21, vcc
	global_load_dwordx4 v[42:45], v[92:93], off offset:-3072 nt
	global_load_dwordx4 v[46:49], v[92:93], off offset:-2048 nt
	global_load_dwordx4 v[50:53], v[92:93], off offset:-1024 nt
	global_load_dwordx4 v[54:57], v[92:93], off nt
	v_add_co_u32_e32 v94, vcc, 0xfffff000, v20
	v_lshl_add_u64 v[18:19], v[18:19], 0, s[2:3]
	s_nop 0
	v_addc_co_u32_e32 v95, vcc, -1, v21, vcc
	global_load_dwordx4 v[58:61], v[94:95], off offset:-3072 nt
	global_load_dwordx4 v[62:65], v[94:95], off offset:-2048 nt
	global_load_dwordx4 v[66:69], v[94:95], off offset:-1024 nt
	global_load_dwordx4 v[70:73], v[20:21], off offset:-4096 nt
	global_load_dwordx4 v[74:77], v[20:21], off offset:-3072 nt
	global_load_dwordx4 v[78:81], v[20:21], off offset:-2048 nt
	global_load_dwordx4 v[82:85], v[20:21], off offset:-1024 nt
	global_load_dwordx4 v[86:89], v[20:21], off nt
	v_cmp_lt_i32_e32 vcc, s1, v16
	s_or_b64 s[6:7], vcc, s[6:7]
	s_waitcnt vmcnt(16)
	v_fmamk_f32 v22, v22, 0x3a800000, v17
	v_fmamk_f32 v23, v23, 0x3a800000, v17
	v_rsq_f32_e32 v22, v22
	v_fmamk_f32 v96, v24, 0x3a800000, v17
	v_rsq_f32_e32 v24, v23
	v_rsq_f32_e32 v96, v96
	s_waitcnt vmcnt(15)
	v_pk_mul_f32 v[28:29], v[28:29], v[22:23] op_sel_hi:[1,0]
	v_pk_mul_f32 v[26:27], v[26:27], v[22:23] op_sel_hi:[1,0]
	s_waitcnt vmcnt(14)
	v_pk_mul_f32 v[32:33], v[32:33], v[22:23] op_sel_hi:[1,0]
	v_pk_mul_f32 v[30:31], v[30:31], v[22:23] op_sel_hi:[1,0]
	s_waitcnt vmcnt(13)
	v_pk_mul_f32 v[36:37], v[36:37], v[22:23] op_sel_hi:[1,0]
	v_pk_mul_f32 v[34:35], v[34:35], v[22:23] op_sel_hi:[1,0]
	s_waitcnt vmcnt(12)
	v_pk_mul_f32 v[40:41], v[40:41], v[22:23] op_sel_hi:[1,0]
	v_pk_mul_f32 v[22:23], v[38:39], v[22:23] op_sel_hi:[1,0]
	s_waitcnt vmcnt(11)
	v_pk_mul_f32 v[44:45], v[44:45], v[24:25] op_sel_hi:[1,0]
	v_pk_mul_f32 v[42:43], v[42:43], v[24:25] op_sel_hi:[1,0]
	s_waitcnt vmcnt(10)
	v_pk_mul_f32 v[48:49], v[48:49], v[24:25] op_sel_hi:[1,0]
	v_pk_mul_f32 v[46:47], v[46:47], v[24:25] op_sel_hi:[1,0]
	s_waitcnt vmcnt(9)
	v_pk_mul_f32 v[52:53], v[52:53], v[24:25] op_sel_hi:[1,0]
	v_pk_mul_f32 v[50:51], v[50:51], v[24:25] op_sel_hi:[1,0]
	s_waitcnt vmcnt(8)
	v_pk_mul_f32 v[56:57], v[56:57], v[24:25] op_sel_hi:[1,0]
	v_pk_mul_f32 v[54:55], v[54:55], v[24:25] op_sel_hi:[1,0]
	s_waitcnt vmcnt(7)
	v_pk_mul_f32 v[60:61], v[60:61], v[96:97] op_sel_hi:[1,0]
	v_pk_mul_f32 v[58:59], v[58:59], v[96:97] op_sel_hi:[1,0]
	s_waitcnt vmcnt(6)
	v_pk_mul_f32 v[64:65], v[64:65], v[96:97] op_sel_hi:[1,0]
	v_pk_mul_f32 v[62:63], v[62:63], v[96:97] op_sel_hi:[1,0]
	v_pk_mul_f32 v[26:27], v[0:1], v[26:27]
	v_pk_mul_f32 v[28:29], v[2:3], v[28:29]
	v_pk_mul_f32 v[30:31], v[4:5], v[30:31]
	v_pk_mul_f32 v[32:33], v[6:7], v[32:33]
	v_pk_mul_f32 v[34:35], v[8:9], v[34:35]
	v_pk_mul_f32 v[36:37], v[10:11], v[36:37]
	v_pk_mul_f32 v[38:39], v[12:13], v[22:23]
	v_pk_mul_f32 v[40:41], v[14:15], v[40:41]
	v_pk_mul_f32 v[42:43], v[0:1], v[42:43]
	v_pk_mul_f32 v[44:45], v[2:3], v[44:45]
	v_pk_mul_f32 v[46:47], v[4:5], v[46:47]
	v_pk_mul_f32 v[48:49], v[6:7], v[48:49]
	v_pk_mul_f32 v[50:51], v[8:9], v[50:51]
	v_pk_mul_f32 v[52:53], v[10:11], v[52:53]
	v_pk_mul_f32 v[54:55], v[12:13], v[54:55]
	v_pk_mul_f32 v[56:57], v[14:15], v[56:57]
	v_pk_mul_f32 v[58:59], v[0:1], v[58:59]
	v_pk_mul_f32 v[60:61], v[2:3], v[60:61]
	v_pk_mul_f32 v[62:63], v[4:5], v[62:63]
	v_pk_mul_f32 v[64:65], v[6:7], v[64:65]
	global_store_dwordx4 v[90:91], v[26:29], off offset:-3072 nt
	global_store_dwordx4 v[90:91], v[30:33], off offset:-2048 nt
	global_store_dwordx4 v[90:91], v[34:37], off offset:-1024 nt
	global_store_dwordx4 v[90:91], v[38:41], off nt
	global_store_dwordx4 v[92:93], v[42:45], off offset:-3072 nt
	global_store_dwordx4 v[92:93], v[46:49], off offset:-2048 nt
	global_store_dwordx4 v[92:93], v[50:53], off offset:-1024 nt
	global_store_dwordx4 v[92:93], v[54:57], off nt
	global_store_dwordx4 v[94:95], v[58:61], off offset:-3072 nt
	global_store_dwordx4 v[94:95], v[62:65], off offset:-2048 nt
	s_waitcnt vmcnt(15)
	v_pk_mul_f32 v[22:23], v[68:69], v[96:97] op_sel_hi:[1,0]
	v_pk_mul_f32 v[26:27], v[66:67], v[96:97] op_sel_hi:[1,0]
	v_pk_mul_f32 v[28:29], v[10:11], v[22:23]
	v_pk_mul_f32 v[26:27], v[8:9], v[26:27]
	v_fmamk_f32 v24, v25, 0x3a800000, v17
	global_store_dwordx4 v[94:95], v[26:29], off offset:-1024 nt
	s_waitcnt vmcnt(15)
	v_pk_mul_f32 v[22:23], v[70:71], v[96:97] op_sel_hi:[1,0]
	v_rsq_f32_e32 v28, v24
	v_pk_mul_f32 v[26:27], v[72:73], v[96:97] op_sel_hi:[1,0]
	v_pk_mul_f32 v[22:23], v[12:13], v[22:23]
	v_pk_mul_f32 v[24:25], v[14:15], v[26:27]
	global_store_dwordx4 v[20:21], v[22:25], off offset:-4096 nt
	s_waitcnt vmcnt(15)
	s_nop 0
	v_pk_mul_f32 v[22:23], v[74:75], v[28:29] op_sel_hi:[1,0]
	v_pk_mul_f32 v[24:25], v[76:77], v[28:29] op_sel_hi:[1,0]
	v_pk_mul_f32 v[22:23], v[0:1], v[22:23]
	v_pk_mul_f32 v[24:25], v[2:3], v[24:25]
	global_store_dwordx4 v[20:21], v[22:25], off offset:-3072 nt
	s_waitcnt vmcnt(15)
	s_nop 0
	v_pk_mul_f32 v[22:23], v[78:79], v[28:29] op_sel_hi:[1,0]
	v_pk_mul_f32 v[24:25], v[80:81], v[28:29] op_sel_hi:[1,0]
	v_pk_mul_f32 v[22:23], v[4:5], v[22:23]
	v_pk_mul_f32 v[24:25], v[6:7], v[24:25]
	global_store_dwordx4 v[20:21], v[22:25], off offset:-2048 nt
	s_waitcnt vmcnt(15)
	s_nop 0
	v_pk_mul_f32 v[22:23], v[82:83], v[28:29] op_sel_hi:[1,0]
	v_pk_mul_f32 v[24:25], v[84:85], v[28:29] op_sel_hi:[1,0]
	v_pk_mul_f32 v[22:23], v[8:9], v[22:23]
	v_pk_mul_f32 v[24:25], v[10:11], v[24:25]
	global_store_dwordx4 v[20:21], v[22:25], off offset:-1024 nt
	s_waitcnt vmcnt(15)
	s_nop 0
	v_pk_mul_f32 v[22:23], v[86:87], v[28:29] op_sel_hi:[1,0]
	v_pk_mul_f32 v[24:25], v[88:89], v[28:29] op_sel_hi:[1,0]
	v_pk_mul_f32 v[22:23], v[12:13], v[22:23]
	v_pk_mul_f32 v[24:25], v[14:15], v[24:25]
	global_store_dwordx4 v[20:21], v[22:25], off nt
	v_lshl_add_u64 v[20:21], v[20:21], 0, s[4:5]
	s_andn2_b64 exec, exec, s[6:7]
	s_cbranch_execnz .LBB0_1858
